# attention: redundant workgroup barrier behind the step loop's closing barrier removed
# baseline (speedup 1.0000x reference)
.LBB0_296:
	s_cmp_lg_u32 s9, 3
	s_cbranch_scc0 .LBB0_298
	s_add_i32 s46, s46, 1
	s_ashr_i32 s34, s46, 3
	v_mov_b32_e32 v72, v152
	s_and_b64 s[0:1], s[0:1], exec
	s_cselect_b32 s48, s78, s77
	v_readfirstlane_b32 s49, v72
	s_lshr_b32 s50, s49, 1
	s_lshl_b32 s48, s48, 7
	s_and_b32 s50, s50, 0x60
	s_ashr_i32 s35, s34, 31
	s_or_b32 s48, s50, s48
	s_lshl_b64 s[0:1], s[34:35], 12
	v_and_or_b32 v64, v72, 31, s48
	v_or_b32_e32 v64, s0, v64
	v_mov_b32_e32 v65, s1
	s_lshl_b32 s46, s46, 7
	v_lshlrev_b64 v[64:65], 11, v[64:65]
	s_and_b32 s50, s46, 0x380
	s_ashr_i32 s48, s49, 2
	v_lshl_add_u64 v[64:65], s[90:91], 0, v[64:65]
	s_lshl_b32 s46, s50, 1
	s_andn2_b32 s48, s48, 63
	v_lshl_add_u64 v[64:65], v[64:65], 0, s[46:47]
	s_ashr_i32 s49, s48, 31
	v_lshl_add_u64 v[64:65], s[48:49], 1, v[64:65]
	v_lshrrev_b32_e32 v66, 1, v72
	s_add_u32 s48, s94, s46
	v_and_b32_e32 v96, 16, v66
	s_addc_u32 s49, s95, 0
	v_lshlrev_b32_e32 v66, 4, v72
	s_lshl_b64 s[34:35], s[34:35], 13
	v_ashrrev_i32_e32 v68, 4, v72
	v_ashrrev_i32_e32 v70, 3, v72
	v_lshl_add_u64 v[64:65], v[64:65], 0, v[96:97]
	v_and_b32_e32 v96, 0xf0, v66
	s_add_u32 s34, s20, s34
	v_ashrrev_i32_e32 v69, 31, v68
	v_add_u32_e32 v70, s50, v70
	global_load_dwordx4 v[98:101], v[64:65], off
	global_load_dwordx4 v[102:105], v[64:65], off offset:32
	global_load_dwordx4 v[106:109], v[64:65], off offset:64
	global_load_dwordx4 v[110:113], v[64:65], off offset:96
	v_lshl_add_u64 v[64:65], s[48:49], 0, v[96:97]
	s_addc_u32 s35, s21, s35
	v_and_b32_e32 v96, 0x70, v66
	v_lshl_add_u64 v[68:69], s[0:1], 0, v[68:69]
	v_ashrrev_i32_e32 v71, 31, v70
	v_lshl_add_u64 v[66:67], s[34:35], 0, v[96:97]
	v_lshlrev_b64 v[68:69], 11, v[68:69]
	v_lshlrev_b64 v[70:71], 15, v[70:71]
	v_lshl_add_u64 v[68:69], v[64:65], 0, v[68:69]
	v_lshl_add_u64 v[70:71], v[66:67], 0, v[70:71]
	global_load_dwordx4 v[118:121], v[68:69], off
	global_load_dwordx4 v[114:117], v[70:71], off
	v_add_u32_e32 v70, 0x200, v72
	v_ashrrev_i32_e32 v68, 4, v70
	v_ashrrev_i32_e32 v69, 31, v68
	v_lshl_add_u64 v[68:69], s[0:1], 0, v[68:69]
	v_lshlrev_b64 v[68:69], 11, v[68:69]
	v_lshl_add_u64 v[64:65], v[64:65], 0, v[68:69]
	v_ashrrev_i32_e32 v68, 3, v70
	v_add_u32_e32 v68, s50, v68
	v_ashrrev_i32_e32 v69, 31, v68
	v_lshlrev_b64 v[68:69], 15, v[68:69]
	v_lshl_add_u64 v[66:67], v[66:67], 0, v[68:69]
	global_load_dwordx4 v[122:125], v[64:65], off
	global_load_dwordx4 v[126:129], v[66:67], off
	s_branch .LBB0_299
